# h5-DA-bias-and-first-V-fragment-reads-hoisted
# baseline (speedup 1.0000x reference)
; __device__ __forceinline__ unsigned cvt_pk_bf16(float lo, float hi) { f32x2_t v = {lo, hi}; bf16x2_t b = __builtin_convertvector(v, bf16x2_t); return __builtin_bit_cast(unsigned, b); }
; __device__ __forceinline__ float max_x32(float v) { auto rr = __builtin_amdgcn_permlane32_swap(__float_as_uint(v), __float_as_uint(v), false, false); return fmaxf(__uint_as_float(rr[0]), __uint_as_float(rr[1])); }
; __device__ __forceinline__ float fast_exp2(float x) { return __builtin_amdgcn_exp2f(x); }
; template <int MODE> ...
;     ...
;             mx = max_x32(mx);
;             const float mnew = fmaxf(mrun, mx);
;             const float alpha = fast_exp2(mrun - mnew);
;             mrun = mnew;
;             float ps = 0.f;
; #pragma unroll
;             for (int r = 0; r < 16; ++r) { s0[r] = fast_exp2(s0[r] - mnew); s1[r] = fast_exp2(s1[r] - mnew); ps += s0[r] + s1[r]; }
;             lsum = lsum * alpha + ps;
; #pragma unroll
;             for (int i = 0; i < NDV; ++i)
; #pragma unroll
;                 for (int r = 0; r < 16; ++r) acc[i][r] *= alpha;
;             bf16x8 pf[2][2];
; #pragma unroll
;             for (int t = 0; t < 2; ++t) {
;                 u32x4 w0, w1;
;                 w0.x = cvt_pk_bf16(s0[8 * t + 0], s0[8 * t + 1]); w0.y = cvt_pk_bf16(s0[8 * t + 2], s0[8 * t + 3]); w0.z = cvt_pk_bf16(s0[8 * t + 4], s0[8 * t + 5]); w0.w = cvt_pk_bf16(s0[8 * t + 6], s0[8 * t + 7]);
;                 w1.x = cvt_pk_bf16(s1[8 * t + 0], s1[8 * t + 1]); w1.y = cvt_pk_bf16(s1[8 * t + 2], s1[8 * t + 3]); w1.z = cvt_pk_bf16(s1[8 * t + 4], s1[8 * t + 5]); w1.w = cvt_pk_bf16(s1[8 * t + 6], s1[8 * t + 7]);
;                 pf[0][t] = __builtin_bit_cast(bf16x8, w0); pf[1][t] = __builtin_bit_cast(bf16x8, w1);
;             }
;     ...
;             {
;                 bf16x8 vcur[4], vnxt[4];
;                 AT_LOADV(vcur, 0);
; #pragma unroll
;                 for (int dvb = 0; dvb < NDV; ++dvb) {
;                     if (dvb + 1 < NDV) AT_LOADV(vnxt, dvb + 1);
;                     __builtin_amdgcn_sched_barrier(0);
; #pragma unroll
;                     for (int i = 0; i < 4; ++i) acc[dvb] = __builtin_amdgcn_mfma_f32_32x32x16_bf16(vcur[i], pf[i >> 1][i & 1], acc[dvb], 0, 0, 0);
.LBB0_386:
	v_add3_u32 v226, s30, v141, v192
	v_add_u32_e32 v226, 0x4000, v226
	ds_read2_b64 v[218:221], v226 offset0:128 offset1:130
	ds_read2_b64 v[222:225], v226 offset0:132 offset1:134
	ds_read2_b64 v[242:245], v226 offset0:136 offset1:138
	ds_read2_b64 v[246:249], v226 offset0:140 offset1:142
	s_nop 8
	v_mov_b32_e32 v80, v0
	s_nop 1
	v_permlane32_swap_b32_e32 v0, v80
	v_max3_f32 v83, v198, v0, v80
	v_max_f32_e32 v211, v0, v80
	v_sub_f32_e32 v211, v211, v198
	v_cmp_lt_f32_e64 s[100:101], 4.0, v211
	s_nop 1
	s_cmp_eq_u64 s[100:101], 0
	s_cbranch_scc0 .Lresc_keep_A
	v_mov_b32_e32 v83, v198
.Lresc_keep_A:
	v_sub_f32_e32 v85, v152, v83
	v_exp_f32_e32 v152, v85
	v_sub_f32_e32 v85, v174, v83
	v_exp_f32_e32 v156, v85
	v_sub_f32_e32 v85, v153, v83
	v_exp_f32_e32 v88, v85
	v_sub_f32_e32 v85, v175, v83
	v_exp_f32_e32 v86, v85
	v_sub_f32_e32 v85, v150, v83
	v_exp_f32_e32 v150, v85
	v_sub_f32_e32 v85, v172, v83
	v_exp_f32_e32 v153, v85
	v_sub_f32_e32 v85, v151, v83
	v_exp_f32_e32 v92, v85
	v_sub_f32_e32 v85, v173, v83
	v_exp_f32_e32 v90, v85
	v_sub_f32_e32 v85, v170, v83
	v_exp_f32_e32 v151, v85
	v_sub_f32_e32 v85, v182, v83
	v_exp_f32_e32 v157, v85
	v_sub_f32_e32 v85, v171, v83
	v_exp_f32_e32 v96, v85
	v_sub_f32_e32 v85, v183, v83
	v_exp_f32_e32 v94, v85
	v_sub_f32_e32 v85, v176, v83
	v_exp_f32_e32 v158, v85
	v_sub_f32_e32 v85, v184, v83
	v_exp_f32_e32 v159, v85
	v_sub_f32_e32 v85, v177, v83
	v_sub_f32_e32 v0, v14, v83
	v_exp_f32_e32 v100, v85
	v_sub_f32_e32 v85, v185, v83
	v_exp_f32_e32 v110, v0
	v_sub_f32_e32 v0, v166, v83
	v_sub_f32_e32 v14, v167, v83
	v_exp_f32_e32 v98, v85
	v_sub_f32_e32 v85, v180, v83
	v_exp_f32_e32 v154, v0
	v_sub_f32_e32 v0, v15, v83
	v_exp_f32_e32 v80, v14
	v_sub_f32_e32 v14, v148, v83
	v_exp_f32_e32 v160, v85
	v_sub_f32_e32 v85, v188, v83
	v_exp_f32_e32 v0, v0
	v_exp_f32_e32 v111, v14
	v_sub_f32_e32 v14, v168, v83
	v_exp_f32_e32 v161, v85
	v_sub_f32_e32 v85, v181, v83
	v_exp_f32_e32 v155, v14
	v_sub_f32_e32 v14, v149, v83
	v_exp_f32_e32 v104, v85
	v_sub_f32_e32 v85, v189, v83
	v_exp_f32_e32 v84, v14
	v_sub_f32_e32 v14, v169, v83
	v_exp_f32_e32 v102, v85
	v_sub_f32_e32 v85, v178, v83
	v_add_f32_e32 v81, v154, v110
	v_exp_f32_e32 v14, v14
	v_exp_f32_e32 v162, v85
	v_sub_f32_e32 v85, v186, v83
	v_exp_f32_e32 v163, v85
	v_sub_f32_e32 v85, v179, v83
	v_pk_add_f32 v[108:109], v[80:81], v[0:1]
	v_exp_f32_e32 v148, v85
	v_sub_f32_e32 v85, v187, v83
	v_pk_add_f32 v[108:109], v[108:109], v[108:109] op_sel_hi:[0,1]
	v_add_f32_e32 v15, v155, v111
	v_exp_f32_e32 v106, v85
	v_mov_b32_e32 v85, v109
	v_pk_add_f32 v[108:109], v[14:15], v[84:85]
	v_add_f32_e32 v87, v156, v152
	v_pk_add_f32 v[108:109], v[108:109], v[108:109] op_sel_hi:[0,1]
	v_mov_b32_e32 v89, v109
	v_pk_add_f32 v[108:109], v[86:87], v[88:89]
	v_add_f32_e32 v91, v153, v150
	v_pk_add_f32 v[108:109], v[108:109], v[108:109] op_sel_hi:[0,1]
	v_mov_b32_e32 v93, v109
	v_pk_add_f32 v[108:109], v[90:91], v[92:93]
	v_add_f32_e32 v95, v157, v151
	v_pk_add_f32 v[108:109], v[108:109], v[108:109] op_sel_hi:[0,1]
	v_mov_b32_e32 v97, v109
	v_pk_add_f32 v[108:109], v[94:95], v[96:97]
	v_add_f32_e32 v99, v159, v158
	v_pk_add_f32 v[108:109], v[108:109], v[108:109] op_sel_hi:[0,1]
	v_mov_b32_e32 v101, v109
	v_pk_add_f32 v[108:109], v[98:99], v[100:101]
	v_add_f32_e32 v103, v161, v160
	v_pk_add_f32 v[108:109], v[108:109], v[108:109] op_sel_hi:[0,1]
	v_mov_b32_e32 v105, v109
	v_pk_add_f32 v[108:109], v[102:103], v[104:105]
	v_add_f32_e32 v107, v163, v162
	v_pk_add_f32 v[108:109], v[108:109], v[108:109] op_sel_hi:[0,1]
	v_mov_b32_e32 v149, v109
	v_pk_add_f32 v[108:109], v[106:107], v[148:149]
	v_cvt_pk_bf16_f32 v87, v153, v90
	v_add_f32_e32 v15, v108, v109
	v_cvt_pk_bf16_f32 v108, v110, v0
	v_cvt_pk_bf16_f32 v109, v111, v84
	v_cvt_pk_bf16_f32 v110, v152, v88
	v_cvt_pk_bf16_f32 v111, v150, v92
	v_cvt_pk_bf16_f32 v88, v151, v96
	v_cvt_pk_bf16_f32 v89, v158, v100
	v_cvt_pk_bf16_f32 v90, v160, v104
	v_cvt_pk_bf16_f32 v91, v162, v148
	v_cvt_pk_bf16_f32 v92, v157, v94
	v_cvt_pk_bf16_f32 v93, v159, v98
	v_cvt_pk_bf16_f32 v94, v161, v102
	v_cvt_pk_bf16_f32 v95, v163, v106
	v_add3_u32 v0, s30, v192, v141
	v_cvt_pk_bf16_f32 v85, v155, v14
	v_add_u32_e32 v14, 0x5000, v0
	v_cvt_pk_bf16_f32 v84, v154, v80
	v_cvt_pk_bf16_f32 v86, v156, v86
	ds_read2_b64 v[152:155], v14 offset0:160 offset1:162
	ds_read2_b64 v[156:159], v14 offset0:164 offset1:166
	ds_read2_b64 v[160:163], v14 offset0:168 offset1:170
	ds_read2_b64 v[164:167], v14 offset0:172 offset1:174
	v_sub_f32_e32 v82, v198, v83
	v_exp_f32_e32 v82, v82
	s_nop 0
	s_cmp_eq_u64 s[100:101], 0
	s_cbranch_scc1 .Lresc_skip_A
	v_pk_mul_f32 v[78:79], v[78:79], v[82:83] op_sel_hi:[1,0]
	v_pk_mul_f32 v[76:77], v[76:77], v[82:83] op_sel_hi:[1,0]
	v_pk_mul_f32 v[74:75], v[74:75], v[82:83] op_sel_hi:[1,0]
	v_pk_mul_f32 v[72:73], v[72:73], v[82:83] op_sel_hi:[1,0]
	v_pk_mul_f32 v[70:71], v[70:71], v[82:83] op_sel_hi:[1,0]
	v_pk_mul_f32 v[68:69], v[68:69], v[82:83] op_sel_hi:[1,0]
	v_pk_mul_f32 v[66:67], v[66:67], v[82:83] op_sel_hi:[1,0]
	v_pk_mul_f32 v[64:65], v[64:65], v[82:83] op_sel_hi:[1,0]
	v_pk_mul_f32 v[62:63], v[62:63], v[82:83] op_sel_hi:[1,0]
	v_pk_mul_f32 v[60:61], v[60:61], v[82:83] op_sel_hi:[1,0]
	v_pk_mul_f32 v[58:59], v[58:59], v[82:83] op_sel_hi:[1,0]
	v_pk_mul_f32 v[56:57], v[56:57], v[82:83] op_sel_hi:[1,0]
	v_pk_mul_f32 v[54:55], v[54:55], v[82:83] op_sel_hi:[1,0]
	v_pk_mul_f32 v[52:53], v[52:53], v[82:83] op_sel_hi:[1,0]
	v_pk_mul_f32 v[50:51], v[50:51], v[82:83] op_sel_hi:[1,0]
	v_pk_mul_f32 v[48:49], v[48:49], v[82:83] op_sel_hi:[1,0]
	v_pk_mul_f32 v[46:47], v[46:47], v[82:83] op_sel_hi:[1,0]
	v_pk_mul_f32 v[44:45], v[44:45], v[82:83] op_sel_hi:[1,0]
	v_pk_mul_f32 v[42:43], v[42:43], v[82:83] op_sel_hi:[1,0]
	v_pk_mul_f32 v[40:41], v[40:41], v[82:83] op_sel_hi:[1,0]
	v_pk_mul_f32 v[38:39], v[38:39], v[82:83] op_sel_hi:[1,0]
	v_pk_mul_f32 v[36:37], v[36:37], v[82:83] op_sel_hi:[1,0]
	v_pk_mul_f32 v[34:35], v[34:35], v[82:83] op_sel_hi:[1,0]
	v_pk_mul_f32 v[32:33], v[32:33], v[82:83] op_sel_hi:[1,0]
	v_pk_mul_f32 v[30:31], v[30:31], v[82:83] op_sel_hi:[1,0]
	v_pk_mul_f32 v[28:29], v[28:29], v[82:83] op_sel_hi:[1,0]
	v_pk_mul_f32 v[26:27], v[26:27], v[82:83] op_sel_hi:[1,0]
	v_pk_mul_f32 v[24:25], v[24:25], v[82:83] op_sel_hi:[1,0]
	v_pk_mul_f32 v[22:23], v[22:23], v[82:83] op_sel_hi:[1,0]
	v_pk_mul_f32 v[20:21], v[20:21], v[82:83] op_sel_hi:[1,0]
	v_pk_mul_f32 v[18:19], v[18:19], v[82:83] op_sel_hi:[1,0]
	v_pk_mul_f32 v[16:17], v[16:17], v[82:83] op_sel_hi:[1,0]
; template <int MODE> ...
;     ...
;             {
;                 bf16x8 vcur[4], vnxt[4];
;                 AT_LOADV(vcur, 0);
; #pragma unroll
;                 for (int dvb = 0; dvb < NDV; ++dvb) {
;                     if (dvb + 1 < NDV) AT_LOADV(vnxt, dvb + 1);
;                     __builtin_amdgcn_sched_barrier(0);
; #pragma unroll
;                     for (int i = 0; i < 4; ++i) acc[dvb] = __builtin_amdgcn_mfma_f32_32x32x16_bf16(vcur[i], pf[i >> 1][i & 1], acc[dvb], 0, 0, 0);
;                     __builtin_amdgcn_sched_barrier(0);
; #pragma unroll
;                     for (int i = 0; i < 4; ++i) vcur[i] = vnxt[i];
;                 }
.Lresc_skip_A:
	s_waitcnt lgkmcnt(7)
	v_mfma_f32_32x32x16_bf16 v[64:79], v[218:221], v[108:111], v[64:79]
	s_waitcnt lgkmcnt(6)
	v_mfma_f32_32x32x16_bf16 v[64:79], v[222:225], v[88:91], v[64:79]
	s_waitcnt lgkmcnt(5)
	v_mfma_f32_32x32x16_bf16 v[64:79], v[242:245], v[84:87], v[64:79]
	s_waitcnt lgkmcnt(4)
	v_mfma_f32_32x32x16_bf16 v[64:79], v[246:249], v[92:95], v[64:79]
	v_add_u32_e32 v14, 0x6000, v0
	ds_read2_b64 v[96:99], v14 offset0:192 offset1:194
	ds_read2_b64 v[100:103], v14 offset0:196 offset1:198
	ds_read2_b64 v[104:107], v14 offset0:200 offset1:202
	ds_read2_b64 v[148:151], v14 offset0:204 offset1:206
	s_waitcnt lgkmcnt(7)
	v_mfma_f32_32x32x16_bf16 v[48:63], v[152:155], v[108:111], v[48:63]
	s_waitcnt lgkmcnt(6)
	v_mfma_f32_32x32x16_bf16 v[48:63], v[156:159], v[88:91], v[48:63]
	s_waitcnt lgkmcnt(5)
	v_mfma_f32_32x32x16_bf16 v[48:63], v[160:163], v[84:87], v[48:63]
	s_waitcnt lgkmcnt(4)
	v_mfma_f32_32x32x16_bf16 v[48:63], v[164:167], v[92:95], v[48:63]
	v_add_u32_e32 v0, 0x7000, v0
	ds_read2_b64 v[152:155], v0 offset0:224 offset1:226
	ds_read2_b64 v[156:159], v0 offset0:228 offset1:230
	ds_read2_b64 v[160:163], v0 offset0:232 offset1:234
	ds_read2_b64 v[164:167], v0 offset0:236 offset1:238
	s_waitcnt lgkmcnt(7)
	v_mfma_f32_32x32x16_bf16 v[32:47], v[96:99], v[108:111], v[32:47]
	s_waitcnt lgkmcnt(6)
	v_mfma_f32_32x32x16_bf16 v[32:47], v[100:103], v[88:91], v[32:47]
	s_waitcnt lgkmcnt(5)
	v_mfma_f32_32x32x16_bf16 v[32:47], v[104:107], v[84:87], v[32:47]
	s_waitcnt lgkmcnt(4)
	v_mfma_f32_32x32x16_bf16 v[32:47], v[148:151], v[92:95], v[32:47]
	s_waitcnt lgkmcnt(3)
	v_mfma_f32_32x32x16_bf16 v[16:31], v[152:155], v[108:111], v[16:31]
	s_waitcnt lgkmcnt(2)
	v_mfma_f32_32x32x16_bf16 v[16:31], v[156:159], v[88:91], v[16:31]
	s_waitcnt lgkmcnt(1)
	v_mfma_f32_32x32x16_bf16 v[16:31], v[160:163], v[84:87], v[16:31]
	s_waitcnt lgkmcnt(0)
	v_mfma_f32_32x32x16_bf16 v[16:31], v[164:167], v[92:95], v[16:31]
	v_fmac_f32_e32 v15, v139, v82
	v_mov_b32_e32 v198, v83
	v_mov_b32_e32 v139, v15

; __device__ __forceinline__ unsigned cvt_pk_bf16(float lo, float hi) { f32x2_t v = {lo, hi}; bf16x2_t b = __builtin_convertvector(v, bf16x2_t); return __builtin_bit_cast(unsigned, b); }
; __device__ __forceinline__ float max_x32(float v) { auto rr = __builtin_amdgcn_permlane32_swap(__float_as_uint(v), __float_as_uint(v), false, false); return fmaxf(__uint_as_float(rr[0]), __uint_as_float(rr[1])); }
; __device__ __forceinline__ float fast_exp2(float x) { return __builtin_amdgcn_exp2f(x); }
; template <int MODE> ...
;     ...
;             mx = max_x32(mx);
;             const float mnew = fmaxf(mrun, mx);
;             const float alpha = fast_exp2(mrun - mnew);
;             mrun = mnew;
;             float ps = 0.f;
; #pragma unroll
;             for (int r = 0; r < 16; ++r) { s0[r] = fast_exp2(s0[r] - mnew); s1[r] = fast_exp2(s1[r] - mnew); ps += s0[r] + s1[r]; }
;             lsum = lsum * alpha + ps;
; #pragma unroll
;             for (int i = 0; i < NDV; ++i)
; #pragma unroll
;                 for (int r = 0; r < 16; ++r) acc[i][r] *= alpha;
;             bf16x8 pf[2][2];
; #pragma unroll
;             for (int t = 0; t < 2; ++t) {
;                 u32x4 w0, w1;
;                 w0.x = cvt_pk_bf16(s0[8 * t + 0], s0[8 * t + 1]); w0.y = cvt_pk_bf16(s0[8 * t + 2], s0[8 * t + 3]); w0.z = cvt_pk_bf16(s0[8 * t + 4], s0[8 * t + 5]); w0.w = cvt_pk_bf16(s0[8 * t + 6], s0[8 * t + 7]);
;                 w1.x = cvt_pk_bf16(s1[8 * t + 0], s1[8 * t + 1]); w1.y = cvt_pk_bf16(s1[8 * t + 2], s1[8 * t + 3]); w1.z = cvt_pk_bf16(s1[8 * t + 4], s1[8 * t + 5]); w1.w = cvt_pk_bf16(s1[8 * t + 6], s1[8 * t + 7]);
;                 pf[0][t] = __builtin_bit_cast(bf16x8, w0); pf[1][t] = __builtin_bit_cast(bf16x8, w1);
;             }
;     ...
;             {
;                 bf16x8 vcur[4], vnxt[4];
;                 AT_LOADV(vcur, 0);
; #pragma unroll
;                 for (int dvb = 0; dvb < NDV; ++dvb) {
;                     if (dvb + 1 < NDV) AT_LOADV(vnxt, dvb + 1);
;                     __builtin_amdgcn_sched_barrier(0);
; #pragma unroll
;                     for (int i = 0; i < 4; ++i) acc[dvb] = __builtin_amdgcn_mfma_f32_32x32x16_bf16(vcur[i], pf[i >> 1][i & 1], acc[dvb], 0, 0, 0);
.LBB0_407:
	v_add3_u32 v226, s12, v194, v141
	v_add_u32_e32 v226, 0x4000, v226
	ds_read2_b64 v[218:221], v226 offset0:128 offset1:130
	ds_read2_b64 v[222:225], v226 offset0:132 offset1:134
	ds_read2_b64 v[242:245], v226 offset0:136 offset1:138
	ds_read2_b64 v[246:249], v226 offset0:140 offset1:142
	s_nop 8
	v_mov_b32_e32 v80, v0
	s_nop 1
	v_permlane32_swap_b32_e32 v0, v80
	v_max3_f32 v83, v196, v0, v80
	v_max_f32_e32 v211, v0, v80
	v_sub_f32_e32 v211, v211, v196
	v_cmp_lt_f32_e64 s[100:101], 4.0, v211
	s_nop 1
	s_cmp_eq_u64 s[100:101], 0
	s_cbranch_scc0 .Lresc_keep_B
	v_mov_b32_e32 v83, v196
.Lresc_keep_B:
	v_sub_f32_e32 v85, v152, v83
	v_exp_f32_e32 v152, v85
	v_sub_f32_e32 v85, v174, v83
	v_exp_f32_e32 v155, v85
	v_sub_f32_e32 v85, v153, v83
	v_exp_f32_e32 v88, v85
	v_sub_f32_e32 v85, v175, v83
	v_exp_f32_e32 v86, v85
	v_sub_f32_e32 v85, v150, v83
	v_exp_f32_e32 v150, v85
	v_sub_f32_e32 v85, v172, v83
	v_exp_f32_e32 v153, v85
	v_sub_f32_e32 v85, v151, v83
	v_exp_f32_e32 v92, v85
	v_sub_f32_e32 v85, v173, v83
	v_exp_f32_e32 v90, v85
	v_sub_f32_e32 v85, v170, v83
	v_exp_f32_e32 v151, v85
	v_sub_f32_e32 v85, v182, v83
	v_exp_f32_e32 v156, v85
	v_sub_f32_e32 v85, v171, v83
	v_exp_f32_e32 v96, v85
	v_sub_f32_e32 v85, v183, v83
	v_exp_f32_e32 v94, v85
	v_sub_f32_e32 v85, v176, v83
	v_exp_f32_e32 v157, v85
	v_sub_f32_e32 v85, v184, v83
	v_exp_f32_e32 v158, v85
	v_sub_f32_e32 v85, v177, v83
	v_sub_f32_e32 v0, v14, v83
	v_exp_f32_e32 v100, v85
	v_sub_f32_e32 v85, v185, v83
	v_exp_f32_e32 v110, v0
	v_sub_f32_e32 v0, v166, v83
	v_sub_f32_e32 v14, v167, v83
	v_exp_f32_e32 v98, v85
	v_sub_f32_e32 v85, v180, v83
	v_exp_f32_e32 v137, v0
	v_sub_f32_e32 v0, v15, v83
	v_exp_f32_e32 v80, v14
	v_sub_f32_e32 v14, v148, v83
	v_exp_f32_e32 v159, v85
	v_sub_f32_e32 v85, v188, v83
	v_exp_f32_e32 v0, v0
	v_exp_f32_e32 v111, v14
	v_sub_f32_e32 v14, v168, v83
	v_exp_f32_e32 v160, v85
	v_sub_f32_e32 v85, v181, v83
	v_exp_f32_e32 v154, v14
	v_sub_f32_e32 v14, v149, v83
	v_exp_f32_e32 v104, v85
	v_sub_f32_e32 v85, v189, v83
	v_exp_f32_e32 v84, v14
	v_sub_f32_e32 v14, v169, v83
	v_exp_f32_e32 v102, v85
	v_sub_f32_e32 v85, v178, v83
	v_add_f32_e32 v81, v137, v110
	v_exp_f32_e32 v14, v14
	v_exp_f32_e32 v161, v85
	v_sub_f32_e32 v85, v186, v83
	v_exp_f32_e32 v162, v85
	v_sub_f32_e32 v85, v179, v83
	v_pk_add_f32 v[108:109], v[80:81], v[0:1]
	v_exp_f32_e32 v148, v85
	v_sub_f32_e32 v85, v187, v83
	v_pk_add_f32 v[108:109], v[108:109], v[108:109] op_sel_hi:[0,1]
	v_add_f32_e32 v15, v154, v111
	v_exp_f32_e32 v106, v85
	v_mov_b32_e32 v85, v109
	v_pk_add_f32 v[108:109], v[14:15], v[84:85]
	v_add_f32_e32 v87, v155, v152
	v_pk_add_f32 v[108:109], v[108:109], v[108:109] op_sel_hi:[0,1]
	v_mov_b32_e32 v89, v109
	v_pk_add_f32 v[108:109], v[86:87], v[88:89]
	v_add_f32_e32 v91, v153, v150
	v_pk_add_f32 v[108:109], v[108:109], v[108:109] op_sel_hi:[0,1]
	v_mov_b32_e32 v93, v109
	v_pk_add_f32 v[108:109], v[90:91], v[92:93]
	v_add_f32_e32 v95, v156, v151
	v_pk_add_f32 v[108:109], v[108:109], v[108:109] op_sel_hi:[0,1]
	v_mov_b32_e32 v97, v109
	v_pk_add_f32 v[108:109], v[94:95], v[96:97]
	v_add_f32_e32 v99, v158, v157
	v_pk_add_f32 v[108:109], v[108:109], v[108:109] op_sel_hi:[0,1]
	v_mov_b32_e32 v101, v109
	v_pk_add_f32 v[108:109], v[98:99], v[100:101]
	v_add_f32_e32 v103, v160, v159
	v_pk_add_f32 v[108:109], v[108:109], v[108:109] op_sel_hi:[0,1]
	v_mov_b32_e32 v105, v109
	v_pk_add_f32 v[108:109], v[102:103], v[104:105]
	v_add_f32_e32 v107, v162, v161
	v_pk_add_f32 v[108:109], v[108:109], v[108:109] op_sel_hi:[0,1]
	v_mov_b32_e32 v149, v109
	v_pk_add_f32 v[108:109], v[106:107], v[148:149]
	v_cvt_pk_bf16_f32 v87, v153, v90
	v_add_f32_e32 v15, v108, v109
	v_cvt_pk_bf16_f32 v108, v110, v0
	v_cvt_pk_bf16_f32 v109, v111, v84
	v_cvt_pk_bf16_f32 v110, v152, v88
	v_cvt_pk_bf16_f32 v111, v150, v92
	v_cvt_pk_bf16_f32 v88, v151, v96
	v_cvt_pk_bf16_f32 v89, v157, v100
	v_cvt_pk_bf16_f32 v90, v159, v104
	v_cvt_pk_bf16_f32 v91, v161, v148
	v_cvt_pk_bf16_f32 v92, v156, v94
	v_cvt_pk_bf16_f32 v93, v158, v98
	v_cvt_pk_bf16_f32 v94, v160, v102
	v_cvt_pk_bf16_f32 v95, v162, v106
	v_add3_u32 v0, s12, v141, v194
	v_cvt_pk_bf16_f32 v85, v154, v14
	v_add_u32_e32 v14, 0x5000, v0
	v_cvt_pk_bf16_f32 v86, v155, v86
	ds_read2_b64 v[152:155], v14 offset0:160 offset1:162
	ds_read2_b64 v[156:159], v14 offset0:164 offset1:166
	ds_read2_b64 v[160:163], v14 offset0:168 offset1:170
	ds_read2_b64 v[164:167], v14 offset0:172 offset1:174
	v_sub_f32_e32 v82, v196, v83
	v_exp_f32_e32 v82, v82
	v_cvt_pk_bf16_f32 v84, v137, v80
	s_cmp_eq_u64 s[100:101], 0
	s_cbranch_scc1 .Lresc_skip_B
	v_pk_mul_f32 v[78:79], v[78:79], v[82:83] op_sel_hi:[1,0]
	v_pk_mul_f32 v[76:77], v[76:77], v[82:83] op_sel_hi:[1,0]
	v_pk_mul_f32 v[74:75], v[74:75], v[82:83] op_sel_hi:[1,0]
	v_pk_mul_f32 v[72:73], v[72:73], v[82:83] op_sel_hi:[1,0]
	v_pk_mul_f32 v[70:71], v[70:71], v[82:83] op_sel_hi:[1,0]
	v_pk_mul_f32 v[68:69], v[68:69], v[82:83] op_sel_hi:[1,0]
	v_pk_mul_f32 v[66:67], v[66:67], v[82:83] op_sel_hi:[1,0]
	v_pk_mul_f32 v[64:65], v[64:65], v[82:83] op_sel_hi:[1,0]
	v_pk_mul_f32 v[62:63], v[62:63], v[82:83] op_sel_hi:[1,0]
	v_pk_mul_f32 v[60:61], v[60:61], v[82:83] op_sel_hi:[1,0]
	v_pk_mul_f32 v[58:59], v[58:59], v[82:83] op_sel_hi:[1,0]
	v_pk_mul_f32 v[56:57], v[56:57], v[82:83] op_sel_hi:[1,0]
	v_pk_mul_f32 v[54:55], v[54:55], v[82:83] op_sel_hi:[1,0]
	v_pk_mul_f32 v[52:53], v[52:53], v[82:83] op_sel_hi:[1,0]
	v_pk_mul_f32 v[50:51], v[50:51], v[82:83] op_sel_hi:[1,0]
	v_pk_mul_f32 v[48:49], v[48:49], v[82:83] op_sel_hi:[1,0]
	v_pk_mul_f32 v[46:47], v[46:47], v[82:83] op_sel_hi:[1,0]
	v_pk_mul_f32 v[44:45], v[44:45], v[82:83] op_sel_hi:[1,0]
	v_pk_mul_f32 v[42:43], v[42:43], v[82:83] op_sel_hi:[1,0]
	v_pk_mul_f32 v[40:41], v[40:41], v[82:83] op_sel_hi:[1,0]
	v_pk_mul_f32 v[38:39], v[38:39], v[82:83] op_sel_hi:[1,0]
	v_pk_mul_f32 v[36:37], v[36:37], v[82:83] op_sel_hi:[1,0]
	v_pk_mul_f32 v[34:35], v[34:35], v[82:83] op_sel_hi:[1,0]
	v_pk_mul_f32 v[32:33], v[32:33], v[82:83] op_sel_hi:[1,0]
	v_pk_mul_f32 v[30:31], v[30:31], v[82:83] op_sel_hi:[1,0]
	v_pk_mul_f32 v[28:29], v[28:29], v[82:83] op_sel_hi:[1,0]
	v_pk_mul_f32 v[26:27], v[26:27], v[82:83] op_sel_hi:[1,0]
	v_pk_mul_f32 v[24:25], v[24:25], v[82:83] op_sel_hi:[1,0]
	v_pk_mul_f32 v[22:23], v[22:23], v[82:83] op_sel_hi:[1,0]
	v_pk_mul_f32 v[20:21], v[20:21], v[82:83] op_sel_hi:[1,0]
	v_pk_mul_f32 v[18:19], v[18:19], v[82:83] op_sel_hi:[1,0]
	v_pk_mul_f32 v[16:17], v[16:17], v[82:83] op_sel_hi:[1,0]
; template <int MODE> ...
;     ...
;             {
;                 bf16x8 vcur[4], vnxt[4];
;                 AT_LOADV(vcur, 0);
; #pragma unroll
;                 for (int dvb = 0; dvb < NDV; ++dvb) {
;                     if (dvb + 1 < NDV) AT_LOADV(vnxt, dvb + 1);
;                     __builtin_amdgcn_sched_barrier(0);
; #pragma unroll
;                     for (int i = 0; i < 4; ++i) acc[dvb] = __builtin_amdgcn_mfma_f32_32x32x16_bf16(vcur[i], pf[i >> 1][i & 1], acc[dvb], 0, 0, 0);
;                     __builtin_amdgcn_sched_barrier(0);
; #pragma unroll
;                     for (int i = 0; i < 4; ++i) vcur[i] = vnxt[i];
;                 }
;             }
.Lresc_skip_B:
	s_waitcnt lgkmcnt(7)
	v_mfma_f32_32x32x16_bf16 v[64:79], v[218:221], v[108:111], v[64:79]
	s_waitcnt lgkmcnt(6)
	v_mfma_f32_32x32x16_bf16 v[64:79], v[222:225], v[88:91], v[64:79]
	s_waitcnt lgkmcnt(5)
	v_mfma_f32_32x32x16_bf16 v[64:79], v[242:245], v[84:87], v[64:79]
	s_waitcnt lgkmcnt(4)
	v_mfma_f32_32x32x16_bf16 v[64:79], v[246:249], v[92:95], v[64:79]
	v_add_u32_e32 v14, 0x6000, v0
	ds_read2_b64 v[96:99], v14 offset0:192 offset1:194
	ds_read2_b64 v[100:103], v14 offset0:196 offset1:198
	ds_read2_b64 v[104:107], v14 offset0:200 offset1:202
	ds_read2_b64 v[148:151], v14 offset0:204 offset1:206
	s_waitcnt lgkmcnt(7)
	v_mfma_f32_32x32x16_bf16 v[48:63], v[152:155], v[108:111], v[48:63]
	s_waitcnt lgkmcnt(6)
	v_mfma_f32_32x32x16_bf16 v[48:63], v[156:159], v[88:91], v[48:63]
	s_waitcnt lgkmcnt(5)
	v_mfma_f32_32x32x16_bf16 v[48:63], v[160:163], v[84:87], v[48:63]
	s_waitcnt lgkmcnt(4)
	v_mfma_f32_32x32x16_bf16 v[48:63], v[164:167], v[92:95], v[48:63]
	v_add_u32_e32 v0, 0x7000, v0
	ds_read2_b64 v[152:155], v0 offset0:224 offset1:226
	ds_read2_b64 v[156:159], v0 offset0:228 offset1:230
	ds_read2_b64 v[160:163], v0 offset0:232 offset1:234
	ds_read2_b64 v[164:167], v0 offset0:236 offset1:238
	s_waitcnt lgkmcnt(7)
	v_mfma_f32_32x32x16_bf16 v[32:47], v[96:99], v[108:111], v[32:47]
	s_waitcnt lgkmcnt(6)
	v_mfma_f32_32x32x16_bf16 v[32:47], v[100:103], v[88:91], v[32:47]
	s_waitcnt lgkmcnt(5)
	v_mfma_f32_32x32x16_bf16 v[32:47], v[104:107], v[84:87], v[32:47]
	s_waitcnt lgkmcnt(4)
	v_mfma_f32_32x32x16_bf16 v[32:47], v[148:151], v[92:95], v[32:47]
	s_waitcnt lgkmcnt(3)
	v_mfma_f32_32x32x16_bf16 v[16:31], v[152:155], v[108:111], v[16:31]
	s_waitcnt lgkmcnt(2)
	v_mfma_f32_32x32x16_bf16 v[16:31], v[156:159], v[88:91], v[16:31]
	s_waitcnt lgkmcnt(1)
	v_mfma_f32_32x32x16_bf16 v[16:31], v[160:163], v[84:87], v[16:31]
	s_waitcnt lgkmcnt(0)
	v_mfma_f32_32x32x16_bf16 v[16:31], v[164:167], v[92:95], v[16:31]
	v_fmac_f32_e32 v15, v139, v82
	v_mov_b32_e32 v196, v83
	v_mov_b32_e32 v139, v15
